# opt19
# baseline (speedup 1.0000x reference)
; __device__ __forceinline__ unsigned xb_ld(unsigned* p) { return __hip_atomic_load(p, __ATOMIC_RELAXED, __HIP_MEMORY_SCOPE_AGENT); }
; __device__ __forceinline__ unsigned xb_add(unsigned* p, unsigned v) { return __hip_atomic_fetch_add(p, v, __ATOMIC_RELAXED, __HIP_MEMORY_SCOPE_AGENT); }
; #define XB_SPIN(cond, bar) do { unsigned _sp = 0; while (cond) { __builtin_amdgcn_s_sleep(1); \
;     if ((++_sp & 255u) == 0u) { if (xb_ld(&(bar)[XB_TMO])) break; if (_sp > XB_SPIN_CAP) { atomicAdd(&(bar)[XB_TMO], 1u); break; } } } } while (0)
; __device__ __forceinline__ void grid_barrier(const Ctx& cx, unsigned* bar, const XcdBar& b) {
;     ...
;       const unsigned og = xb_add(&bar[XB_TOP], 1u);
;       const unsigned tg = og / b.nx;
;       if (og + 1u == (tg + 1u) * b.nx) xb_add(&bar[XB_TOPGEN], 1u);
;       else XB_SPIN(xb_ld(&bar[XB_TOPGEN]) == tg, bar);
.LBB0_1479:
	s_or_b64 exec, exec, s[8:9]
	s_waitcnt vmcnt(0)
	v_readfirstlane_b32 s6, v1
	s_nop 1
	v_add_u32_e32 v1, s6, v0
	v_mul_hi_u32 v0, v1, v155
	v_readlane_b32 s6, v254, 5
	v_add_u32_e32 v4, 1, v0
	s_nop 0
	v_mul_lo_u32 v2, v0, s6
	v_sub_u32_e32 v2, v1, v2
	v_cmp_le_u32_e32 vcc, s6, v2
	v_add_u32_e32 v1, 1, v1
	s_nop 0
	v_cndmask_b32_e32 v0, v0, v4, vcc
	v_subrev_u32_e32 v4, s6, v2
	v_cndmask_b32_e32 v2, v2, v4, vcc
	v_add_u32_e32 v4, 1, v0
	v_cmp_le_u32_e32 vcc, s6, v2
	s_nop 1
	v_cndmask_b32_e32 v0, v0, v4, vcc
	v_mul_lo_u32 v2, s6, v0
	v_add_u32_e32 v2, s6, v2
	v_cmp_ne_u32_e32 vcc, v1, v2
	s_and_saveexec_b64 s[6:7], vcc
	s_xor_b64 s[6:7], exec, s[6:7]
	s_cbranch_execz .LBB0_1493
	v_readlane_b32 s8, v254, 7
	v_readlane_b32 s9, v254, 8
	s_lshl_b64 s[8:9], s[8:9], 2
	s_waitcnt lgkmcnt(0)
	s_add_u32 s10, s0, 0x3500
	s_addc_u32 s11, s1, 0
	global_load_dword v1, v3, s[10:11] sc1
	s_waitcnt vmcnt(0)
	v_cmp_eq_u32_e32 vcc, v1, v0
	s_and_saveexec_b64 s[8:9], vcc
	s_cbranch_execz .LBB0_1492
	s_mov_b32 s22, 1
	s_mov_b64 s[12:13], 0
	s_branch .LBB0_1483
